# differential attention role-split loop: leading wave half waits for its last K-fragment LDS reads behind the MFMA segment's closing barrier instead of in front of it (slot is rewritten only after the
# baseline (speedup 1.0000x reference)
.Lpqk2A:
	v_add_f32_e32 v230, v98, v99
	v_cvt_pk_bf16_f32 v150, v98, v99
	v_add_f32_e32 v231, v100, v101
	v_cvt_pk_bf16_f32 v151, v100, v101
	v_add_f32_e32 v230, v102, v230
	v_add_f32_e32 v231, v103, v231
	v_add_f32_e32 v230, v104, v230
	v_cvt_pk_bf16_f32 v152, v102, v103
	v_add_f32_e32 v231, v105, v231
	v_cvt_pk_bf16_f32 v153, v104, v105
	v_add_f32_e32 v230, v106, v230
	v_add_f32_e32 v231, v107, v231
	v_add_f32_e32 v230, v108, v230
	v_cvt_pk_bf16_f32 v10, v106, v107
	v_add_f32_e32 v231, v109, v231
	v_cvt_pk_bf16_f32 v11, v108, v109
	v_add_f32_e32 v230, v110, v230
	v_add_f32_e32 v231, v111, v231
	v_add_f32_e32 v230, v112, v230
	v_cvt_pk_bf16_f32 v12, v110, v111
	v_add_f32_e32 v231, v113, v231
	v_cvt_pk_bf16_f32 v13, v112, v113
	v_add_f32_e32 v230, v82, v230
	v_add_f32_e32 v231, v83, v231
	v_add_f32_e32 v230, v84, v230
	v_cvt_pk_bf16_f32 v6, v82, v83
	v_add_f32_e32 v231, v85, v231
	v_cvt_pk_bf16_f32 v7, v84, v85
	v_add_f32_e32 v230, v86, v230
	v_add_f32_e32 v231, v87, v231
	v_add_f32_e32 v230, v88, v230
	v_cvt_pk_bf16_f32 v8, v86, v87
	v_add_f32_e32 v231, v89, v231
	v_cvt_pk_bf16_f32 v9, v88, v89
	v_add_f32_e32 v230, v90, v230
	v_add_f32_e32 v231, v91, v231
	v_add_f32_e32 v230, v92, v230
	v_cvt_pk_bf16_f32 v2, v90, v91
	v_add_f32_e32 v231, v93, v231
	v_cvt_pk_bf16_f32 v3, v92, v93
	v_add_f32_e32 v230, v94, v230
	v_add_f32_e32 v231, v95, v231
	v_add_f32_e32 v230, v96, v230
	v_cvt_pk_bf16_f32 v4, v94, v95
	v_add_f32_e32 v231, v97, v231
	v_cvt_pk_bf16_f32 v5, v96, v97
	v_add_f32_e32 v230, v230, v231
	v_add_f32_e32 v206, v232, v230
	s_barrier
	s_setprio 1
	v_add_u32_e32 v0, s22, v251
	ds_read_b64_tr_b16 v[198:199], v0 offset:24576
	ds_read_b64_tr_b16 v[200:201], v0 offset:25088
	s_waitcnt lgkmcnt(9)
	v_mfma_f32_32x32x16_bf16 v[130:145], v[194:197], v[162:165], v[208:223]
	ds_read_b64_tr_b16 v[194:195], v0 offset:28672
	ds_read_b64_tr_b16 v[196:197], v0 offset:29184
	s_waitcnt lgkmcnt(10)
	v_mfma_f32_32x32x16_bf16 v[114:129], v[186:189], v[162:165], v[208:223]
	ds_read_b64_tr_b16 v[102:103], v0 offset:25600
	ds_read_b64_tr_b16 v[104:105], v0 offset:26112
	s_waitcnt lgkmcnt(11)
	v_mfma_f32_32x32x16_bf16 v[130:145], v[190:193], v[158:161], v[130:145]
	ds_read_b64_tr_b16 v[98:99], v0 offset:29696
	ds_read_b64_tr_b16 v[100:101], v0 offset:30208
	s_waitcnt lgkmcnt(12)
	v_mfma_f32_32x32x16_bf16 v[114:129], v[182:185], v[158:161], v[114:129]
	ds_read_b64_tr_b16 v[110:111], v0 offset:26624
	ds_read_b64_tr_b16 v[112:113], v0 offset:27136
	s_waitcnt lgkmcnt(13)
	v_mfma_f32_32x32x16_bf16 v[130:145], v[178:181], v[154:157], v[130:145]
	ds_read_b64_tr_b16 v[106:107], v0 offset:30720
	ds_read_b64_tr_b16 v[108:109], v0 offset:31232
	s_waitcnt lgkmcnt(14)
	v_mfma_f32_32x32x16_bf16 v[114:129], v[174:177], v[154:157], v[114:129]
	ds_read_b64_tr_b16 v[86:87], v0 offset:27648
	ds_read_b64_tr_b16 v[88:89], v0 offset:28160
	s_waitcnt lgkmcnt(14)
	v_mfma_f32_32x32x16_bf16 v[130:145], v[170:173], v[146:149], v[130:145]
	ds_read_b64_tr_b16 v[82:83], v0 offset:31744
	ds_read_b64_tr_b16 v[84:85], v0 offset:32256
	v_mfma_f32_32x32x16_bf16 v[114:129], v[166:169], v[146:149], v[114:129]
	s_add_u32 s54, s48, s14
	s_addc_u32 s55, s49, s15
	s_add_u32 s56, s54, 0x8000
	s_addc_u32 s57, s55, 0
	s_add_i32 s16, s21, s43
	s_mov_b32 m0, s16
	s_nop 0
	global_load_lds_dwordx4 v202, s[56:57]
	s_add_u32 s56, s50, s14
	s_addc_u32 s57, s51, s15
	s_add_u32 s56, s56, 0x4000
	s_addc_u32 s57, s57, 0
	s_add_i32 s16, s13, s44
	s_mov_b32 m0, s16
	s_nop 0
	global_load_lds_dwordx4 v203, s[56:57]
	s_add_u32 s58, s52, s14
	s_addc_u32 s59, s53, s15
	s_add_u32 s58, s58, 0x4000
	s_addc_u32 s59, s59, 0
	s_add_i32 s16, s13, s45
	s_mov_b32 m0, s16
	s_nop 0
	global_load_lds_dwordx4 v203, s[58:59]
	v_add_u32_e32 v0, s22, v249
	v_add_u32_e32 v166, 0xe800, v0
	s_waitcnt lgkmcnt(14)
	v_mfma_f32_32x32x16_bf16 v[66:81], v[150:153], v[198:201], v[66:81]
	ds_read_b64_tr_b16 v[90:91], v0 offset:59392
	ds_read_b64_tr_b16 v[92:93], v0 offset:59904
	s_waitcnt lgkmcnt(14)
	v_mfma_f32_32x32x16_bf16 v[50:65], v[150:153], v[194:197], v[50:65]
	ds_read_b64_tr_b16 v[94:95], v0 offset:63488
	ds_read_b64_tr_b16 v[96:97], v0 offset:64000
	s_waitcnt lgkmcnt(14)
	v_mfma_f32_32x32x16_bf16 v[66:81], v[10:13], v[102:105], v[66:81]
	ds_read_b64_tr_b16 v[102:103], v0 offset:60416
	ds_read_b64_tr_b16 v[104:105], v0 offset:60928
	s_waitcnt lgkmcnt(14)
	v_mfma_f32_32x32x16_bf16 v[50:65], v[10:13], v[98:101], v[50:65]
	ds_read_b64_tr_b16 v[98:99], v0 offset:64512
	ds_read_b64_tr_b16 v[100:101], v0 offset:65024
	s_waitcnt lgkmcnt(14)
	v_mfma_f32_32x32x16_bf16 v[66:81], v[6:9], v[110:113], v[66:81]
	ds_read_b64_tr_b16 v[110:111], v0 offset:61440
	ds_read_b64_tr_b16 v[112:113], v0 offset:61952
	s_waitcnt lgkmcnt(14)
	v_mfma_f32_32x32x16_bf16 v[50:65], v[6:9], v[106:109], v[50:65]
	ds_read_b64_tr_b16 v[106:107], v166 offset:6144
	ds_read_b64_tr_b16 v[108:109], v166 offset:6656
	s_waitcnt lgkmcnt(14)
	v_mfma_f32_32x32x16_bf16 v[66:81], v[2:5], v[86:89], v[66:81]
	ds_read_b64_tr_b16 v[190:191], v0 offset:62464
	ds_read_b64_tr_b16 v[192:193], v0 offset:62976
	s_waitcnt lgkmcnt(14)
	v_mfma_f32_32x32x16_bf16 v[50:65], v[2:5], v[82:85], v[50:65]
	ds_read_b64_tr_b16 v[194:195], v166 offset:7168
	ds_read_b64_tr_b16 v[196:197], v166 offset:7680
	s_waitcnt lgkmcnt(14)
	v_mfma_f32_32x32x16_bf16 v[34:49], v[150:153], v[90:93], v[34:49]
	s_waitcnt lgkmcnt(12)
	v_mfma_f32_32x32x16_bf16 v[18:33], v[150:153], v[94:97], v[18:33]
	v_add_u32_e32 v0, s13, v250
	ds_read_b128 v[86:89], v0
	ds_read_b128 v[82:85], v0 offset:512
	s_waitcnt lgkmcnt(12)
	v_mfma_f32_32x32x16_bf16 v[34:49], v[10:13], v[102:105], v[34:49]
	ds_read_b128 v[186:189], v0 offset:2048
	ds_read_b128 v[182:185], v0 offset:2560
	s_waitcnt lgkmcnt(12)
	v_mfma_f32_32x32x16_bf16 v[18:33], v[10:13], v[98:101], v[18:33]
	ds_read_b128 v[178:181], v0 offset:4096
	ds_read_b128 v[174:177], v0 offset:4608
	s_waitcnt lgkmcnt(12)
	v_mfma_f32_32x32x16_bf16 v[34:49], v[6:9], v[110:113], v[34:49]
	ds_read_b128 v[170:173], v0 offset:6144
	ds_read_b128 v[166:169], v0 offset:6656
	s_waitcnt lgkmcnt(12)
	v_mfma_f32_32x32x16_bf16 v[18:33], v[6:9], v[106:109], v[18:33]
	s_waitcnt lgkmcnt(10)
	v_mfma_f32_32x32x16_bf16 v[34:49], v[2:5], v[190:193], v[34:49]
	s_waitcnt lgkmcnt(8)
	v_mfma_f32_32x32x16_bf16 v[18:33], v[2:5], v[194:197], v[18:33]
	s_setprio 0
	s_waitcnt vmcnt(3)
	s_barrier
	s_waitcnt lgkmcnt(0)
	v_exp_f32_e32 v130, v130
	v_exp_f32_e32 v131, v131
	v_exp_f32_e32 v132, v132
	v_exp_f32_e32 v133, v133
	v_exp_f32_e32 v134, v134
	v_exp_f32_e32 v135, v135
	v_exp_f32_e32 v136, v136
	v_exp_f32_e32 v137, v137
	v_exp_f32_e32 v138, v138
	v_exp_f32_e32 v139, v139
	v_exp_f32_e32 v140, v140
	v_exp_f32_e32 v141, v141
	v_exp_f32_e32 v142, v142
	v_exp_f32_e32 v143, v143
	v_exp_f32_e32 v144, v144
	v_exp_f32_e32 v145, v145
	v_exp_f32_e32 v114, v114
	v_exp_f32_e32 v115, v115
	v_exp_f32_e32 v116, v116
	v_exp_f32_e32 v117, v117
	v_exp_f32_e32 v118, v118
	v_exp_f32_e32 v119, v119
	v_exp_f32_e32 v120, v120
	v_exp_f32_e32 v121, v121
	v_exp_f32_e32 v122, v122
	v_exp_f32_e32 v123, v123
	v_exp_f32_e32 v124, v124
	v_exp_f32_e32 v125, v125
	v_exp_f32_e32 v126, v126
	v_exp_f32_e32 v127, v127
	v_exp_f32_e32 v128, v128
	v_exp_f32_e32 v129, v129
	v_add_f32_e32 v230, v130, v131
	v_cvt_pk_bf16_f32 v150, v130, v131
	v_add_f32_e32 v231, v132, v133
	v_cvt_pk_bf16_f32 v151, v132, v133
	v_add_f32_e32 v230, v134, v230
	v_add_f32_e32 v231, v135, v231
	v_add_f32_e32 v230, v136, v230
	v_cvt_pk_bf16_f32 v152, v134, v135
	v_add_f32_e32 v231, v137, v231
	v_cvt_pk_bf16_f32 v153, v136, v137
	v_add_f32_e32 v230, v138, v230
	v_add_f32_e32 v231, v139, v231
	v_add_f32_e32 v230, v140, v230
	v_cvt_pk_bf16_f32 v10, v138, v139
	v_add_f32_e32 v231, v141, v231
	v_cvt_pk_bf16_f32 v11, v140, v141
	v_add_f32_e32 v230, v142, v230
	v_add_f32_e32 v231, v143, v231
	v_add_f32_e32 v230, v144, v230
	v_cvt_pk_bf16_f32 v12, v142, v143
	v_add_f32_e32 v231, v145, v231
	v_cvt_pk_bf16_f32 v13, v144, v145
	v_add_f32_e32 v230, v114, v230
	v_add_f32_e32 v231, v115, v231
	v_add_f32_e32 v230, v116, v230
	v_cvt_pk_bf16_f32 v6, v114, v115
	v_add_f32_e32 v231, v117, v231
	v_cvt_pk_bf16_f32 v7, v116, v117
	v_add_f32_e32 v230, v118, v230
	v_add_f32_e32 v231, v119, v231
	v_add_f32_e32 v230, v120, v230
	v_cvt_pk_bf16_f32 v8, v118, v119
	v_add_f32_e32 v231, v121, v231
	v_cvt_pk_bf16_f32 v9, v120, v121
	v_add_f32_e32 v230, v122, v230
	v_add_f32_e32 v231, v123, v231
	v_add_f32_e32 v230, v124, v230
	v_cvt_pk_bf16_f32 v2, v122, v123
	v_add_f32_e32 v231, v125, v231
	v_cvt_pk_bf16_f32 v3, v124, v125
	v_add_f32_e32 v230, v126, v230
	v_add_f32_e32 v231, v127, v231
	v_add_f32_e32 v230, v128, v230
	v_cvt_pk_bf16_f32 v4, v126, v127
	v_add_f32_e32 v231, v129, v231
	v_cvt_pk_bf16_f32 v5, v128, v129
	v_add_f32_e32 v230, v230, v231
	v_add_f32_e32 v232, v206, v230
	s_barrier
;   #define WB(a,b) do{ if constexpr(DV2){WAIT_BAR(b);} else {WAIT_BAR(a);} }while(0)
;   #define RESC() do{ if(resc){ asm volatile("s_waitcnt lgkmcnt(0)":::"memory"); \
;       _Pragma("unroll") for(int d_=0;d_<ND;++d_) _Pragma("unroll") for(int r=0;r<16;++r)o[d_][r]*=wsf[crow(r,hi)]; } }while(0)
;   #define ROT() do{sl_prev=sl_cur;sl_cur=sl_next;sl_next=(sl_next==(NSLOT-1)*SLOTB)?0:sl_next+SLOTB;}while(0)
;     ...
;   int t=1;
;   for(;t+5<NT;t+=2){
;     STEP(pB0,pB1,pA0,pA1,t,true,true,true);     WB(2,3); RESC(); ROT();
;     STEP(pA0,pA1,pB0,pB1,t+1,true,true,true);   WB(2,3); RESC(); ROT();
;   }
	s_setprio 1
	s_add_i32 s16, s13, 0x2000
	s_cmpk_lg_i32 s13, 0x4000
	s_cselect_b32 s47, s16, 0
	v_add_u32_e32 v207, s21, v251
	ds_read_b64_tr_b16 v[198:199], v207 offset:24576
	ds_read_b64_tr_b16 v[200:201], v207 offset:25088
	s_waitcnt lgkmcnt(9)
	v_mfma_f32_32x32x16_bf16 v[98:113], v[86:89], v[162:165], v[208:223]
	ds_read_b64_tr_b16 v[194:195], v207 offset:28672
	ds_read_b64_tr_b16 v[196:197], v207 offset:29184
	s_waitcnt lgkmcnt(10)
	v_mfma_f32_32x32x16_bf16 v[82:97], v[82:85], v[162:165], v[208:223]
	ds_read_b64_tr_b16 v[190:191], v207 offset:25600
	ds_read_b64_tr_b16 v[192:193], v207 offset:26112
	s_waitcnt lgkmcnt(11)
	v_mfma_f32_32x32x16_bf16 v[98:113], v[186:189], v[158:161], v[98:113]
	ds_read_b64_tr_b16 v[138:139], v207 offset:29696
	ds_read_b64_tr_b16 v[140:141], v207 offset:30208
	s_waitcnt lgkmcnt(12)
	v_mfma_f32_32x32x16_bf16 v[82:97], v[182:185], v[158:161], v[82:97]
	ds_read_b64_tr_b16 v[134:135], v207 offset:26624
	ds_read_b64_tr_b16 v[136:137], v207 offset:27136
	s_waitcnt lgkmcnt(13)
	v_mfma_f32_32x32x16_bf16 v[98:113], v[178:181], v[154:157], v[98:113]
	ds_read_b64_tr_b16 v[130:131], v207 offset:30720
	ds_read_b64_tr_b16 v[132:133], v207 offset:31232
	s_waitcnt lgkmcnt(14)
	v_mfma_f32_32x32x16_bf16 v[82:97], v[174:177], v[154:157], v[82:97]
	ds_read_b64_tr_b16 v[118:119], v207 offset:27648
	ds_read_b64_tr_b16 v[120:121], v207 offset:28160
	s_waitcnt lgkmcnt(14)
	v_mfma_f32_32x32x16_bf16 v[98:113], v[170:173], v[146:149], v[98:113]
	ds_read_b64_tr_b16 v[114:115], v207 offset:31744
	ds_read_b64_tr_b16 v[116:117], v207 offset:32256
	v_mfma_f32_32x32x16_bf16 v[82:97], v[166:169], v[146:149], v[82:97]
	s_add_u32 s56, s54, 0xa000
	s_addc_u32 s57, s55, 0
	s_add_i32 s16, s13, s43
	s_mov_b32 m0, s16
	s_nop 0
	global_load_lds_dwordx4 v202, s[56:57]
	s_add_u32 s56, s50, s14
	s_addc_u32 s57, s51, s15
	s_add_u32 s56, s56, 0x6000
	s_addc_u32 s57, s57, 0
	s_add_i32 s16, s47, s44
	s_mov_b32 m0, s16
	s_nop 0
	global_load_lds_dwordx4 v203, s[56:57]
	s_add_u32 s58, s52, s14
	s_addc_u32 s59, s53, s15
	s_add_u32 s58, s58, 0x6000
	s_addc_u32 s59, s59, 0
	s_add_i32 s16, s47, s45
	s_mov_b32 m0, s16
	s_nop 0
	global_load_lds_dwordx4 v203, s[58:59]
	v_add_u32_e32 v14, s21, v249
	v_add_u32_e32 v15, 0xe800, v14
	s_waitcnt lgkmcnt(14)
	v_mfma_f32_32x32x16_bf16 v[66:81], v[150:153], v[198:201], v[66:81]
	ds_read_b64_tr_b16 v[122:123], v14 offset:59392
	ds_read_b64_tr_b16 v[124:125], v14 offset:59904
	s_waitcnt lgkmcnt(14)
	v_mfma_f32_32x32x16_bf16 v[50:65], v[150:153], v[194:197], v[50:65]
	ds_read_b64_tr_b16 v[126:127], v14 offset:63488
	ds_read_b64_tr_b16 v[128:129], v14 offset:64000
	s_waitcnt lgkmcnt(14)
	v_mfma_f32_32x32x16_bf16 v[66:81], v[10:13], v[190:193], v[66:81]
	ds_read_b64_tr_b16 v[142:143], v14 offset:60416
	ds_read_b64_tr_b16 v[144:145], v14 offset:60928
	s_waitcnt lgkmcnt(14)
	v_mfma_f32_32x32x16_bf16 v[50:65], v[10:13], v[138:141], v[50:65]
	ds_read_b64_tr_b16 v[138:139], v14 offset:64512
	ds_read_b64_tr_b16 v[140:141], v14 offset:65024
	s_waitcnt lgkmcnt(14)
	v_mfma_f32_32x32x16_bf16 v[66:81], v[6:9], v[134:137], v[66:81]
	ds_read_b64_tr_b16 v[134:135], v14 offset:61440
	ds_read_b64_tr_b16 v[136:137], v14 offset:61952
	s_waitcnt lgkmcnt(14)
	v_mfma_f32_32x32x16_bf16 v[50:65], v[6:9], v[130:133], v[50:65]
	ds_read_b64_tr_b16 v[130:131], v15 offset:6144
	ds_read_b64_tr_b16 v[132:133], v15 offset:6656
	s_waitcnt lgkmcnt(14)
	v_mfma_f32_32x32x16_bf16 v[66:81], v[2:5], v[118:121], v[66:81]
	ds_read_b64_tr_b16 v[118:119], v14 offset:62464
	ds_read_b64_tr_b16 v[120:121], v14 offset:62976
	s_waitcnt lgkmcnt(14)
	v_mfma_f32_32x32x16_bf16 v[50:65], v[2:5], v[114:117], v[50:65]
	ds_read_b64_tr_b16 v[114:115], v15 offset:7168
	ds_read_b64_tr_b16 v[116:117], v15 offset:7680
	s_waitcnt lgkmcnt(14)
	v_mfma_f32_32x32x16_bf16 v[34:49], v[150:153], v[122:125], v[34:49]
	s_waitcnt lgkmcnt(12)
	v_mfma_f32_32x32x16_bf16 v[18:33], v[150:153], v[126:129], v[18:33]
	v_add_u32_e32 v14, s47, v250
	ds_read_b128 v[194:197], v14
	ds_read_b128 v[186:189], v14 offset:512
	s_waitcnt lgkmcnt(12)
	v_mfma_f32_32x32x16_bf16 v[34:49], v[10:13], v[142:145], v[34:49]
	ds_read_b128 v[190:193], v14 offset:2048
	ds_read_b128 v[182:185], v14 offset:2560
	s_waitcnt lgkmcnt(12)
	v_mfma_f32_32x32x16_bf16 v[18:33], v[10:13], v[138:141], v[18:33]
	ds_read_b128 v[178:181], v14 offset:4096
	ds_read_b128 v[174:177], v14 offset:4608
	s_waitcnt lgkmcnt(12)
	v_mfma_f32_32x32x16_bf16 v[34:49], v[6:9], v[134:137], v[34:49]
	ds_read_b128 v[170:173], v14 offset:6144
	ds_read_b128 v[166:169], v14 offset:6656
	s_waitcnt lgkmcnt(12)
	v_mfma_f32_32x32x16_bf16 v[18:33], v[6:9], v[130:133], v[18:33]
	s_waitcnt lgkmcnt(10)
	v_mfma_f32_32x32x16_bf16 v[34:49], v[2:5], v[118:121], v[34:49]
	s_waitcnt lgkmcnt(8)
	v_mfma_f32_32x32x16_bf16 v[18:33], v[2:5], v[114:117], v[18:33]
	s_setprio 0
	s_waitcnt vmcnt(3)
	s_barrier
	s_waitcnt lgkmcnt(0)
	v_exp_f32_e32 v98, v98
	v_exp_f32_e32 v99, v99
	v_exp_f32_e32 v100, v100
	v_exp_f32_e32 v101, v101
	v_exp_f32_e32 v102, v102
	v_exp_f32_e32 v103, v103
	v_exp_f32_e32 v104, v104
	v_exp_f32_e32 v105, v105
	v_exp_f32_e32 v106, v106
	v_exp_f32_e32 v107, v107
	v_exp_f32_e32 v108, v108
	v_exp_f32_e32 v109, v109
	v_exp_f32_e32 v110, v110
	v_exp_f32_e32 v111, v111
	v_exp_f32_e32 v112, v112
	v_exp_f32_e32 v113, v113
	v_exp_f32_e32 v82, v82
	v_exp_f32_e32 v83, v83
	v_exp_f32_e32 v84, v84
	v_exp_f32_e32 v85, v85
	v_exp_f32_e32 v86, v86
	v_exp_f32_e32 v87, v87
	v_exp_f32_e32 v88, v88
	v_exp_f32_e32 v89, v89
	v_exp_f32_e32 v90, v90
	v_exp_f32_e32 v91, v91
	v_exp_f32_e32 v92, v92
	v_exp_f32_e32 v93, v93
	v_exp_f32_e32 v94, v94
	v_exp_f32_e32 v95, v95
	v_exp_f32_e32 v96, v96
	v_exp_f32_e32 v97, v97
	s_add_i32 s16, s47, 0x2000
	s_cmpk_lg_i32 s47, 0x4000
	s_cselect_b32 s46, s16, 0
	s_add_i32 s16, s20, 2
	s_add_u32 s14, s14, 0x4000
	s_addc_u32 s15, s15, 0
	s_cmp_ge_u32 s16, s39
	s_cbranch_scc1 .Lpqk2A_exit
	s_mov_b32 s20, s16
	s_mov_b32 s22, s13
	s_mov_b32 s21, s47
	s_mov_b32 s13, s46
	s_branch .Lpqk2A
